# P5 combine stores written through (sc0 sc1) so the XCC's last arriver has little left to write back at the split P5->P6 seam
# speedup vs baseline: 1.0006x; 1.0006x over previous
; __device__ __forceinline__ unsigned pk2(float lo, float hi) { return f2bf(lo) | (f2bf(hi) << 16); }
; __device__ __forceinline__ float bflo(unsigned u) { return __uint_as_float(u << 16); }
; __device__ __forceinline__ float bfhi(unsigned u) { return __uint_as_float(u & 0xffff0000u); }
; __device__ __forceinline__ float silu_f(float v) { return v / (1.f + __expf(-v)); }
; __device__ __forceinline__ void ph_combine(const Params& p_) {
;     ...
;         for (int u = 0; u < 2; ++u) if (act[u]) { f32x4 s = ce[u];
;             if (use_so[u]) s = (kv[u] <= 2048) ? s - so[u] : s + so[u];
;             const float alt = (kv[u] & 1) ? -1.f : 1.f;
; #pragma unroll
;             for (int j = 0; j < 4; ++j) s[j] += alt * pv[u][j];
;             u32x2 w; w.x = pk2(s[0] * silu_f(bflo(gz[u].x)), s[1] * silu_f(bfhi(gz[u].x))); w.y = pk2(s[2] * silu_f(bflo(gz[u].y)), s[3] * silu_f(bfhi(gz[u].y)));
;             *(u32x2*)(CAT + (size_t)rowv[u] * DM + c4v[u]) = w; }
.LBB0_662:
	s_or_b64 exec, exec, s[38:39]
	v_lshlrev_b32_e32 v0, 16, v30
	v_lshlrev_b32_e32 v6, 16, v32
	v_lshlrev_b32_e32 v10, 16, v31
	v_lshlrev_b32_e32 v11, 16, v33
	v_lshlrev_b32_e32 v13, 16, v26
	v_cndmask_b32_e64 v7, -v6, v6, s[42:43]
	v_cndmask_b32_e64 v6, -v0, v0, s[42:43]
	v_mov_b32_e32 v8, v2
	v_mov_b32_e32 v9, v4
	v_and_b32_e32 v15, 0xffff0000, v26
	v_pk_add_f32 v[6:7], v[6:7], v[8:9]
	v_cndmask_b32_e64 v9, -v11, v11, s[42:43]
	v_cndmask_b32_e64 v8, -v10, v10, s[42:43]
	v_mov_b32_e32 v4, v3
	v_mul_f32_e32 v0, 0xbfb8aa3b, v13
	v_lshlrev_b32_e32 v12, 16, v27
	v_pk_add_f32 v[2:3], v[8:9], v[4:5]
	v_exp_f32_e32 v4, v0
	v_mul_f32_e32 v0, 0xbfb8aa3b, v15
	v_exp_f32_e32 v8, v0
	v_mul_f32_e32 v0, 0xbfb8aa3b, v12
	v_exp_f32_e32 v5, v0
	v_and_b32_e32 v14, 0xffff0000, v27
	v_ashrrev_i32_e32 v19, 31, v18
	v_pk_add_f32 v[4:5], v[4:5], 1.0 op_sel_hi:[1,0]
	s_nop 0
	v_div_scale_f32 v0, s[12:13], v5, v5, v12
	v_rcp_f32_e32 v9, v0
	s_nop 0
	v_fma_f32 v10, -v0, v9, 1.0
	v_fmac_f32_e32 v9, v10, v9
	v_div_scale_f32 v10, vcc, v12, v5, v12
	v_mul_f32_e32 v11, v10, v9
	v_fma_f32 v16, -v0, v11, v10
	v_fmac_f32_e32 v11, v16, v9
	v_fma_f32 v0, -v0, v11, v10
	v_div_fmas_f32 v0, v0, v9, v11
	v_div_fixup_f32 v5, v0, v5, v12
	v_div_scale_f32 v0, s[12:13], v4, v4, v13
	v_rcp_f32_e32 v9, v0
	s_nop 0
	v_fma_f32 v10, -v0, v9, 1.0
	v_fmac_f32_e32 v9, v10, v9
	v_div_scale_f32 v10, vcc, v13, v4, v13
	v_mul_f32_e32 v11, v10, v9
	v_fma_f32 v12, -v0, v11, v10
	v_fmac_f32_e32 v11, v12, v9
	v_fma_f32 v0, -v0, v11, v10
	v_div_fmas_f32 v0, v0, v9, v11
	v_div_fixup_f32 v4, v0, v4, v13
	v_mul_f32_e32 v0, 0xbfb8aa3b, v14
	v_exp_f32_e32 v9, v0
	v_pk_mul_f32 v[4:5], v[4:5], v[6:7]
	v_pk_add_f32 v[6:7], v[8:9], 1.0 op_sel_hi:[1,0]
	s_nop 0
	v_div_scale_f32 v0, s[12:13], v7, v7, v14
	v_rcp_f32_e32 v8, v0
	s_nop 0
	v_fma_f32 v9, -v0, v8, 1.0
	v_fmac_f32_e32 v8, v9, v8
	v_div_scale_f32 v9, vcc, v14, v7, v14
	v_mul_f32_e32 v10, v9, v8
	v_fma_f32 v11, -v0, v10, v9
	v_fmac_f32_e32 v10, v11, v8
	v_fma_f32 v0, -v0, v10, v9
	v_div_fmas_f32 v0, v0, v8, v10
	v_div_fixup_f32 v7, v0, v7, v14
	v_div_scale_f32 v0, s[12:13], v6, v6, v15
	v_rcp_f32_e32 v8, v0
	s_nop 0
	v_fma_f32 v9, -v0, v8, 1.0
	v_fmac_f32_e32 v8, v9, v8
	v_div_scale_f32 v9, vcc, v15, v6, v15
	v_mul_f32_e32 v10, v9, v8
	v_fma_f32 v11, -v0, v10, v9
	v_fmac_f32_e32 v10, v11, v8
	v_fma_f32 v0, -v0, v10, v9
	v_div_fmas_f32 v0, v0, v8, v10
	v_div_fixup_f32 v6, v0, v6, v15
	v_pk_mul_f32 v[2:3], v[6:7], v[2:3]
	v_and_b32_sdwa v6, v4, v179 dst_sel:DWORD dst_unused:UNUSED_PAD src0_sel:WORD_1 src1_sel:DWORD
	v_and_b32_sdwa v0, v5, v179 dst_sel:DWORD dst_unused:UNUSED_PAD src0_sel:WORD_1 src1_sel:DWORD
	v_add3_u32 v4, v4, v6, s14
	v_and_b32_sdwa v6, v2, v179 dst_sel:DWORD dst_unused:UNUSED_PAD src0_sel:WORD_1 src1_sel:DWORD
	v_add3_u32 v0, v5, v0, s14
	v_and_b32_sdwa v5, v3, v179 dst_sel:DWORD dst_unused:UNUSED_PAD src0_sel:WORD_1 src1_sel:DWORD
	v_add3_u32 v2, v2, v6, s14
	v_add3_u32 v3, v3, v5, s14
	v_and_b32_e32 v2, 0xffff0000, v2
	v_and_b32_e32 v3, 0xffff0000, v3
	v_or_b32_sdwa v2, v2, v4 dst_sel:DWORD dst_unused:UNUSED_PAD src0_sel:DWORD src1_sel:WORD_1
	v_lshlrev_b64 v[4:5], 12, v[18:19]
	v_or_b32_sdwa v3, v3, v0 dst_sel:DWORD dst_unused:UNUSED_PAD src0_sel:DWORD src1_sel:WORD_1
	v_lshl_add_u64 v[4:5], s[56:57], 0, v[4:5]
	v_lshlrev_b32_e32 v0, 1, v20
	v_lshl_add_u64 v[4:5], v[4:5], 0, v[0:1]
	global_store_dwordx2 v[4:5], v[2:3], off offset:3072 sc0 sc1

; __device__ __forceinline__ unsigned pk2(float lo, float hi) { return f2bf(lo) | (f2bf(hi) << 16); }
; __device__ __forceinline__ float bf2f(bf16 b) { return __uint_as_float((unsigned)b << 16); }
; __device__ __forceinline__ float bflo(unsigned u) { return __uint_as_float(u << 16); }
; __device__ __forceinline__ float bfhi(unsigned u) { return __uint_as_float(u & 0xffff0000u); }
; __device__ __forceinline__ float silu_f(float v) { return v / (1.f + __expf(-v)); }
; __device__ __forceinline__ void ph_combine(const Params& p_) {
;     ...
;         for (int u = 0; u < 2; ++u) { const int e = e0 + u * nth; act[u] = e < MTOK * DG / 4; const int ee = act[u] ? e : e0;
;             const int row = ee >> 7, c4 = (ee & 127) * 4, b = row >> 12, k = row & 4095, kk = (k <= 2048) ? k : 4096 - k;
;             rowv[u] = row; c4v[u] = c4; kv[u] = k; use_so[u] = (kk != 0 && kk != 2048);
;             ce[u] = (kk == 2048) ? *(const f32x4*)(Ce + (size_t)(2 * 2304 + 2 * 2048) * 512 + b * 512 + c4) : *(const f32x4*)(Ce + ((size_t)b * 2304 + kk) * 512 + c4);
;             so[u] = *(const f32x4*)(So + ((size_t)b * 2048 + (use_so[u] ? kk : 1)) * 512 + c4);
;             gz[u] = *(const u32x2*)(Z + (size_t)row * DIN + DG + c4);
; #pragma unroll
;             for (int j = 0; j < 4; ++j) pv[u][j] = bf2f(PQ[((size_t)(b * 512 + c4 + j) * 2) * 4096 + 2048]); }
;         asm volatile("" ::: "memory");
; #pragma unroll
;         for (int u = 0; u < 2; ++u) if (act[u]) { f32x4 s = ce[u];
;             if (use_so[u]) s = (kv[u] <= 2048) ? s - so[u] : s + so[u];
;             const float alt = (kv[u] & 1) ? -1.f : 1.f;
; #pragma unroll
;             for (int j = 0; j < 4; ++j) s[j] += alt * pv[u][j];
;             u32x2 w; w.x = pk2(s[0] * silu_f(bflo(gz[u].x)), s[1] * silu_f(bfhi(gz[u].x))); w.y = pk2(s[2] * silu_f(bflo(gz[u].y)), s[3] * silu_f(bfhi(gz[u].y)));
;             *(u32x2*)(CAT + (size_t)rowv[u] * DM + c4v[u]) = w; }
.LBB0_678:
	s_or_b64 exec, exec, s[44:45]
	s_waitcnt vmcnt(0)
	v_cndmask_b32_e64 v35, v200, v204, s[26:27]
	v_cndmask_b32_e64 v34, v201, v205, s[26:27]
	v_cndmask_b32_e64 v37, v202, v206, s[26:27]
	v_cndmask_b32_e64 v36, v203, v207, s[26:27]
	v_cndmask_b32_e64 v30, v200, v204, s[54:55]
	v_cndmask_b32_e64 v31, v201, v205, s[54:55]
	v_cndmask_b32_e64 v32, v202, v206, s[54:55]
	v_cndmask_b32_e64 v33, v203, v207, s[54:55]
	v_and_b32_e32 v15, 0x80, v19
	v_lshlrev_b32_e32 v0, 16, v35
	v_lshlrev_b32_e32 v14, 16, v37
	v_cmp_eq_u32_e64 s[42:43], 0, v15
	v_lshlrev_b32_e32 v34, 16, v34
	v_lshlrev_b32_e32 v35, 16, v36
	v_lshlrev_b32_e32 v36, 16, v28
	v_cndmask_b32_e64 v15, -v14, v14, s[42:43]
	v_cndmask_b32_e64 v14, -v0, v0, s[42:43]
	v_mov_b32_e32 v16, v10
	v_mov_b32_e32 v17, v12
	v_and_b32_e32 v28, 0xffff0000, v28
	v_pk_add_f32 v[14:15], v[14:15], v[16:17]
	v_cndmask_b32_e64 v17, -v35, v35, s[42:43]
	v_cndmask_b32_e64 v16, -v34, v34, s[42:43]
	v_mov_b32_e32 v12, v11
	v_mul_f32_e32 v0, 0xbfb8aa3b, v36
	v_lshlrev_b32_e32 v19, 16, v29
	v_pk_add_f32 v[10:11], v[16:17], v[12:13]
	v_exp_f32_e32 v12, v0
	v_mul_f32_e32 v0, 0xbfb8aa3b, v28
	v_exp_f32_e32 v16, v0
	v_mul_f32_e32 v0, 0xbfb8aa3b, v19
	v_exp_f32_e32 v13, v0
	v_and_b32_e32 v29, 0xffff0000, v29
	v_ashrrev_i32_e32 v25, 31, v24
	v_pk_add_f32 v[12:13], v[12:13], 1.0 op_sel_hi:[1,0]
	s_nop 0
	v_div_scale_f32 v0, s[12:13], v13, v13, v19
	v_rcp_f32_e32 v17, v0
	s_nop 0
	v_fma_f32 v34, -v0, v17, 1.0
	v_fmac_f32_e32 v17, v34, v17
	v_div_scale_f32 v34, vcc, v19, v13, v19
	v_mul_f32_e32 v35, v34, v17
	v_fma_f32 v37, -v0, v35, v34
	v_fmac_f32_e32 v35, v37, v17
	v_fma_f32 v0, -v0, v35, v34
	v_div_fmas_f32 v0, v0, v17, v35
	v_div_fixup_f32 v13, v0, v13, v19
	v_div_scale_f32 v0, s[12:13], v12, v12, v36
	v_rcp_f32_e32 v17, v0
	s_nop 0
	v_fma_f32 v19, -v0, v17, 1.0
	v_fmac_f32_e32 v17, v19, v17
	v_div_scale_f32 v19, vcc, v36, v12, v36
	v_mul_f32_e32 v34, v19, v17
	v_fma_f32 v35, -v0, v34, v19
	v_fmac_f32_e32 v34, v35, v17
	v_fma_f32 v0, -v0, v34, v19
	v_div_fmas_f32 v0, v0, v17, v34
	v_div_fixup_f32 v12, v0, v12, v36
	v_mul_f32_e32 v0, 0xbfb8aa3b, v29
	v_exp_f32_e32 v17, v0
	v_pk_mul_f32 v[12:13], v[12:13], v[14:15]
	v_pk_add_f32 v[14:15], v[16:17], 1.0 op_sel_hi:[1,0]
	s_nop 0
	v_div_scale_f32 v0, s[12:13], v15, v15, v29
	v_rcp_f32_e32 v16, v0
	s_nop 0
	v_fma_f32 v17, -v0, v16, 1.0
	v_fmac_f32_e32 v16, v17, v16
	v_div_scale_f32 v17, vcc, v29, v15, v29
	v_mul_f32_e32 v19, v17, v16
	v_fma_f32 v34, -v0, v19, v17
	v_fmac_f32_e32 v19, v34, v16
	v_fma_f32 v0, -v0, v19, v17
	v_div_fmas_f32 v0, v0, v16, v19
	v_div_fixup_f32 v15, v0, v15, v29
	v_div_scale_f32 v0, s[12:13], v14, v14, v28
	v_rcp_f32_e32 v16, v0
	s_nop 0
	v_fma_f32 v17, -v0, v16, 1.0
	v_fmac_f32_e32 v16, v17, v16
	v_div_scale_f32 v17, vcc, v28, v14, v28
	v_mul_f32_e32 v19, v17, v16
	v_fma_f32 v29, -v0, v19, v17
	v_fmac_f32_e32 v19, v29, v16
	v_fma_f32 v0, -v0, v19, v17
	v_div_fmas_f32 v0, v0, v16, v19
	v_div_fixup_f32 v14, v0, v14, v28
	v_pk_mul_f32 v[10:11], v[14:15], v[10:11]
	v_and_b32_sdwa v14, v12, v179 dst_sel:DWORD dst_unused:UNUSED_PAD src0_sel:WORD_1 src1_sel:DWORD
	v_and_b32_sdwa v0, v13, v179 dst_sel:DWORD dst_unused:UNUSED_PAD src0_sel:WORD_1 src1_sel:DWORD
	v_add3_u32 v12, v12, v14, s14
	v_and_b32_sdwa v14, v10, v179 dst_sel:DWORD dst_unused:UNUSED_PAD src0_sel:WORD_1 src1_sel:DWORD
	v_add3_u32 v0, v13, v0, s14
	v_and_b32_sdwa v13, v11, v179 dst_sel:DWORD dst_unused:UNUSED_PAD src0_sel:WORD_1 src1_sel:DWORD
	v_add3_u32 v10, v10, v14, s14
	v_add3_u32 v11, v11, v13, s14
	v_and_b32_e32 v10, 0xffff0000, v10
	v_and_b32_e32 v11, 0xffff0000, v11
	v_or_b32_sdwa v10, v10, v12 dst_sel:DWORD dst_unused:UNUSED_PAD src0_sel:DWORD src1_sel:WORD_1
	v_lshlrev_b64 v[12:13], 12, v[24:25]
	v_or_b32_sdwa v11, v11, v0 dst_sel:DWORD dst_unused:UNUSED_PAD src0_sel:DWORD src1_sel:WORD_1
	v_lshl_add_u64 v[12:13], s[56:57], 0, v[12:13]
	v_lshlrev_b32_e32 v0, 1, v22
	v_lshl_add_u64 v[12:13], v[12:13], 0, v[0:1]
	global_store_dwordx2 v[12:13], v[10:11], off offset:3072 sc0 sc1
	s_and_saveexec_b64 s[44:45], s[38:39]
	s_cbranch_execz .LBB0_663
	s_and_saveexec_b64 s[38:39], s[40:41]
	s_cbranch_execz .LBB0_662
	s_and_saveexec_b64 s[12:13], s[36:37]
	s_xor_b64 s[36:37], exec, s[12:13]
	v_pk_add_f32 v[4:5], v[4:5], v[8:9]
	v_pk_add_f32 v[2:3], v[2:3], v[6:7]
	s_andn2_saveexec_b64 s[36:37], s[36:37]
	s_cbranch_execz .LBB0_661
	v_sub_f32_e32 v5, v5, v9
	v_sub_f32_e32 v4, v4, v8
	v_sub_f32_e32 v3, v3, v7
	v_sub_f32_e32 v2, v2, v6
	s_branch .LBB0_661
